# layer-1 w_in transposes moved from P1-L1 into the idle tails of P5-L0 and P6-L0 (workgroups without a third tile)
# baseline (speedup 1.0000x reference)
.LBB0_86:
	s_or_b64 exec, exec, s[0:1]
	v_readlane_b32 s22, v250, 19
	v_readlane_b32 s23, v250, 20
	s_xor_b64 s[0:1], s[22:23], -1
	v_readlane_b32 s14, v252, 51
	v_readlane_b32 s15, v252, 52
	v_writelane_b32 v250, s0, 23
	s_andn2_b64 vcc, exec, s[0:1]
	s_nop 0
	v_writelane_b32 v250, s1, 24
	s_cbranch_vccnz .LBB0_89
	v_readlane_b32 s0, v252, 33
	v_readlane_b32 s1, v252, 34
	s_andn2_b64 vcc, exec, s[0:1]
	v_readlane_b32 s4, v251, 51
	s_mov_b32 s5, s92
	s_barrier
	s_branch .LBB0_89

.LBB0_470:
	v_readlane_b32 s28, v250, 12
	v_readlane_b32 s26, v250, 15
	v_readlane_b32 s29, v250, 13
	v_readlane_b32 s27, v250, 16
	s_mov_b32 s70, 0x800000
	s_barrier
	v_readlane_b32 s0, v250, 19
	v_readlane_b32 s1, v250, 20
	s_cmp_lt_u32 s92, 64
	s_cbranch_scc1 .Ltra_skip
	s_and_b64 vcc, exec, s[0:1]
	s_cbranch_vccz .Ltra_skip
	v_readlane_b32 s17, v250, 6
	v_readlane_b32 s20, v250, 7
	v_readlane_b32 s32, v250, 4
	v_readlane_b32 s35, v250, 5
	s_mov_b32 s10, 0xf000
	s_movk_i32 s11, 0x204
	s_mov_b32 s12, 0x5040100
	s_add_i32 s5, s92, -64
	s_add_i32 s7, s5, 961
.Ltra_loop:
	s_lshl_b32 s4, s5, 8
	s_mul_hi_i32 s0, s5, 0x88888889
	s_add_i32 s0, s0, s5
	s_lshr_b32 s1, s0, 31
	s_ashr_i32 s6, s0, 5
	s_add_i32 s6, s6, s1
	s_mul_i32 s1, s6, 0xffffc400
	s_add_i32 s8, s4, s1
	s_ashr_i32 s9, s8, 31
	s_lshl_b32 s0, s6, 6
	v_mov_b32_e32 v7, v1
	s_lshl_b64 s[8:9], s[8:9], 2
	s_add_u32 s8, s17, s8
	v_lshlrev_b32_e32 v2, 4, v7
	v_add_u32_e32 v24, 0x800, v7
	s_addc_u32 s9, s20, s9
	v_and_b32_e32 v194, 0x3f0, v2
	v_ashrrev_i32_e32 v40, 6, v7
	v_ashrrev_i32_e32 v44, 6, v24
	v_lshl_add_u64 v[2:3], s[8:9], 0, v[194:195]
	v_add_u32_e32 v4, s0, v40
	v_add_u32_e32 v41, 0x200, v7
	v_add_u32_e32 v24, s0, v44
	v_add_u32_e32 v28, 0xa00, v7
	v_mad_i64_i32 v[4:5], s[8:9], v4, s10, v[2:3]
	v_ashrrev_i32_e32 v42, 6, v41
	v_mad_i64_i32 v[24:25], s[8:9], v24, s10, v[2:3]
	v_ashrrev_i32_e32 v45, 6, v28
	global_load_dwordx4 v[8:11], v[4:5], off
	v_add_u32_e32 v6, 0x400, v7
	global_load_dwordx4 v[24:27], v[24:25], off
	v_add_u32_e32 v4, s0, v42
	v_add_u32_e32 v28, s0, v45
	v_add_u32_e32 v32, 0xc00, v7
	v_mad_i64_i32 v[4:5], s[8:9], v4, s10, v[2:3]
	v_ashrrev_i32_e32 v43, 6, v6
	v_mad_i64_i32 v[28:29], s[8:9], v28, s10, v[2:3]
	v_ashrrev_i32_e32 v46, 6, v32
	global_load_dwordx4 v[12:15], v[4:5], off
	v_add_u32_e32 v32, s0, v46
	global_load_dwordx4 v[28:31], v[28:29], off
	v_add_u32_e32 v4, s0, v43
	v_mad_i64_i32 v[4:5], s[8:9], v4, s10, v[2:3]
	v_mad_i64_i32 v[32:33], s[8:9], v32, s10, v[2:3]
	global_load_dwordx4 v[16:19], v[4:5], off
	v_add_u32_e32 v36, 0xe00, v7
	global_load_dwordx4 v[32:35], v[32:33], off
	v_add_u32_e32 v4, 0x600, v7
	v_ashrrev_i32_e32 v5, 6, v4
	v_ashrrev_i32_e32 v47, 6, v36
	v_add_u32_e32 v20, s0, v5
	v_add_u32_e32 v36, s0, v47
	v_mad_i64_i32 v[20:21], s[8:9], v20, s10, v[2:3]
	v_mad_i64_i32 v[2:3], s[8:9], v36, s10, v[2:3]
	v_lshlrev_b32_e32 v48, 3, v7
	global_load_dwordx4 v[20:23], v[20:21], off
	v_ashrrev_i32_e32 v7, 3, v7
	global_load_dwordx4 v[36:39], v[2:3], off
	v_and_b32_e32 v2, 0x1f8, v48
	s_waitcnt vmcnt(0)
	v_cvt_pk_bf16_f32 v3, v8, v9
	s_ashr_i32 s1, s0, 31
	v_mad_u64_u32 v[8:9], s[8:9], v40, s11, v[2:3]
	ds_write_b32 v8, v3
	v_cvt_pk_bf16_f32 v3, v10, v11
	ds_write_b32 v8, v3 offset:4
	s_waitcnt vmcnt(5)
	v_cvt_pk_bf16_f32 v3, v12, v13
	s_mulk_i32 s6, 0x3c00
	v_mad_u64_u32 v[8:9], s[8:9], v42, s11, v[2:3]
	ds_write_b32 v8, v3
	v_cvt_pk_bf16_f32 v3, v14, v15
	ds_write_b32 v8, v3 offset:4
	s_waitcnt vmcnt(3)
	v_cvt_pk_bf16_f32 v3, v16, v17
	s_lshl_b64 s[0:1], s[0:1], 1
	v_mad_u64_u32 v[8:9], s[8:9], v43, s11, v[2:3]
	ds_write_b32 v8, v3
	v_cvt_pk_bf16_f32 v3, v18, v19
	ds_write_b32 v8, v3 offset:4
	s_waitcnt vmcnt(1)
	v_cvt_pk_bf16_f32 v3, v20, v21
	s_add_u32 s0, s32, s0
	v_mad_u64_u32 v[8:9], s[8:9], v5, s11, v[2:3]
	ds_write_b32 v8, v3
	v_cvt_pk_bf16_f32 v3, v22, v23
	ds_write_b32 v8, v3 offset:4
	v_cvt_pk_bf16_f32 v3, v24, v25
	s_addc_u32 s1, s35, s1
	v_mad_u64_u32 v[8:9], s[8:9], v44, s11, v[2:3]
	ds_write_b32 v8, v3
	v_cvt_pk_bf16_f32 v3, v26, v27
	ds_write_b32 v8, v3 offset:4
	v_cvt_pk_bf16_f32 v3, v28, v29
	s_add_i32 s5, s5, 0xc0
	v_mad_u64_u32 v[8:9], s[8:9], v45, s11, v[2:3]
	ds_write_b32 v8, v3
	v_cvt_pk_bf16_f32 v3, v30, v31
	ds_write_b32 v8, v3 offset:4
	v_cvt_pk_bf16_f32 v3, v32, v33
	s_nop 0
	v_mad_u64_u32 v[8:9], s[8:9], v46, s11, v[2:3]
	ds_write_b32 v8, v3
	v_cvt_pk_bf16_f32 v3, v34, v35
	ds_write_b32 v8, v3 offset:4
	s_waitcnt vmcnt(0)
	v_cvt_pk_bf16_f32 v5, v36, v37
	v_mad_u64_u32 v[2:3], s[8:9], v47, s11, v[2:3]
	ds_write_b32 v2, v5
	v_and_b32_e32 v5, 56, v48
	v_lshlrev_b32_e32 v194, 1, v5
	v_mul_u32_u24_e32 v5, 0x204, v5
	v_lshl_add_u32 v8, v7, 1, v5
	v_cvt_pk_bf16_f32 v3, v38, v39
	ds_write_b32 v2, v3 offset:4
	s_waitcnt lgkmcnt(0)
	s_barrier
	ds_read_u16 v12, v8
	ds_read_u16 v13, v8 offset:516
	ds_read_u16 v9, v8 offset:1032
	ds_read_u16 v14, v8 offset:1548
	ds_read_u16 v10, v8 offset:2064
	ds_read_u16 v15, v8 offset:2580
	ds_read_u16 v11, v8 offset:3096
	ds_read_u16 v8, v8 offset:3612
	v_subrev_u32_e32 v7, s6, v7
	v_lshl_add_u64 v[2:3], s[0:1], 0, v[194:195]
	s_waitcnt lgkmcnt(2)
	v_perm_b32 v10, v15, v10, s12
	v_perm_b32 v9, v14, v9, s12
	s_waitcnt lgkmcnt(0)
	v_perm_b32 v11, v8, v11, s12
	v_perm_b32 v8, v13, v12, s12
	v_add_u32_e32 v12, s4, v7
	v_ashrrev_i32_e32 v13, 31, v12
	v_lshlrev_b64 v[12:13], 12, v[12:13]
	v_lshl_add_u64 v[12:13], v[2:3], 0, v[12:13]
	v_ashrrev_i32_e32 v7, 3, v41
	global_store_dwordx4 v[12:13], v[8:11], off
	s_nop 1
	v_lshl_add_u32 v8, v7, 1, v5
	ds_read_u16 v12, v8
	ds_read_u16 v13, v8 offset:516
	ds_read_u16 v9, v8 offset:1032
	ds_read_u16 v14, v8 offset:1548
	ds_read_u16 v10, v8 offset:2064
	ds_read_u16 v15, v8 offset:2580
	ds_read_u16 v11, v8 offset:3096
	ds_read_u16 v8, v8 offset:3612
	v_subrev_u32_e32 v7, s6, v7
	s_waitcnt lgkmcnt(4)
	v_perm_b32 v9, v14, v9, s12
	s_waitcnt lgkmcnt(2)
	v_perm_b32 v10, v15, v10, s12
	s_waitcnt lgkmcnt(0)
	v_perm_b32 v11, v8, v11, s12
	v_perm_b32 v8, v13, v12, s12
	v_add_u32_e32 v12, s4, v7
	v_ashrrev_i32_e32 v13, 31, v12
	v_lshlrev_b64 v[12:13], 12, v[12:13]
	v_lshl_add_u64 v[12:13], v[2:3], 0, v[12:13]
	global_store_dwordx4 v[12:13], v[8:11], off
	s_nop 1
	v_ashrrev_i32_e32 v10, 3, v6
	v_lshl_add_u32 v6, v10, 1, v5
	ds_read_u16 v11, v6
	ds_read_u16 v12, v6 offset:516
	ds_read_u16 v7, v6 offset:1032
	ds_read_u16 v13, v6 offset:1548
	ds_read_u16 v8, v6 offset:2064
	ds_read_u16 v14, v6 offset:2580
	ds_read_u16 v9, v6 offset:3096
	ds_read_u16 v6, v6 offset:3612
	v_subrev_u32_e32 v10, s6, v10
	v_add_u32_e32 v10, s4, v10
	s_waitcnt lgkmcnt(2)
	v_perm_b32 v8, v14, v8, s12
	v_perm_b32 v7, v13, v7, s12
	s_waitcnt lgkmcnt(0)
	v_perm_b32 v9, v6, v9, s12
	v_perm_b32 v6, v12, v11, s12
	v_ashrrev_i32_e32 v11, 31, v10
	v_lshlrev_b64 v[10:11], 12, v[10:11]
	v_lshl_add_u64 v[10:11], v[2:3], 0, v[10:11]
	global_store_dwordx4 v[10:11], v[6:9], off
	s_nop 1
	v_ashrrev_i32_e32 v8, 3, v4
	v_lshl_add_u32 v4, v8, 1, v5
	ds_read_u16 v9, v4
	ds_read_u16 v10, v4 offset:516
	ds_read_u16 v5, v4 offset:1032
	ds_read_u16 v11, v4 offset:1548
	ds_read_u16 v6, v4 offset:2064
	ds_read_u16 v12, v4 offset:2580
	ds_read_u16 v7, v4 offset:3096
	ds_read_u16 v4, v4 offset:3612
	v_subrev_u32_e32 v8, s6, v8
	v_add_u32_e32 v8, s4, v8
	s_waitcnt lgkmcnt(2)
	v_perm_b32 v6, v12, v6, s12
	s_waitcnt lgkmcnt(0)
	v_perm_b32 v7, v4, v7, s12
	v_perm_b32 v4, v10, v9, s12
	v_ashrrev_i32_e32 v9, 31, v8
	v_lshlrev_b64 v[8:9], 12, v[8:9]
	v_perm_b32 v5, v11, v5, s12
	v_lshl_add_u64 v[2:3], v[2:3], 0, v[8:9]
	s_cmp_lt_i32 s5, s7
	global_store_dwordx4 v[2:3], v[4:7], off
	s_barrier
	s_cbranch_scc1 .Ltra_loop
.Ltra_skip:
.LBB0_471:
	v_mov_b32_e32 v2, v1
	s_waitcnt vmcnt(0)
	s_nop 0
	v_and_b32_e32 v3, 63, v2
	v_readfirstlane_b32 s5, v2
	v_cmp_eq_u32_e32 vcc, 0, v3
	s_and_saveexec_b64 s[0:1], vcc
	s_cbranch_execz .LBB0_474
	s_mov_b64 s[8:9], exec
	v_mbcnt_lo_u32_b32 v2, s8, 0
	v_mbcnt_hi_u32_b32 v2, s9, v2
	v_cmp_eq_u32_e64 s[6:7], 0, v2
	s_and_b64 s[6:7], exec, s[6:7]
	s_mov_b64 exec, s[6:7]
	s_bcnt1_i32_b64 s4, s[8:9]
	v_mov_b32_e32 v2, s4
	ds_add_u32 v196, v2

.LBB0_508:
	v_readlane_b32 s20, v250, 10
	v_readlane_b32 s21, v250, 11
	s_mov_b32 s34, 0x5040100
	s_barrier
	v_readlane_b32 s0, v250, 19
	v_readlane_b32 s1, v250, 20
	s_cmp_lt_u32 s92, 64
	s_cbranch_scc1 .Ltrb_skip
	s_and_b64 vcc, exec, s[0:1]
	s_cbranch_vccz .Ltrb_skip
	v_readlane_b32 s17, v250, 6
	v_readlane_b32 s20, v250, 7
	v_readlane_b32 s32, v250, 4
	v_readlane_b32 s35, v250, 5
	s_mov_b32 s10, 0xf000
	s_movk_i32 s11, 0x204
	s_mov_b32 s12, 0x5040100
	s_add_i32 s5, s92, 1088
	s_add_i32 s7, s5, 577

.Ltrb_skip:
.LBB0_509:
	v_readlane_b32 s0, v250, 27
	v_readlane_b32 s1, v250, 28
	s_and_b64 vcc, exec, s[0:1]
	s_mov_b64 s[0:1], -1
	v_readlane_b32 s17, v250, 6
	v_readlane_b32 s20, v250, 7
	v_readlane_b32 s24, v250, 14
	s_mov_b32 s25, 0xf000
	s_movk_i32 s33, 0x204
	s_cbranch_vccnz .LBB0_80
	v_mov_b32_e32 v2, v1
	s_waitcnt vmcnt(0)
	s_nop 0
	v_and_b32_e32 v3, 63, v2
	v_readfirstlane_b32 s8, v2
	v_cmp_eq_u32_e32 vcc, 0, v3
	s_and_saveexec_b64 s[4:5], vcc
	s_cbranch_execz .LBB0_513
	s_mov_b64 s[6:7], exec
	v_mbcnt_lo_u32_b32 v2, s6, 0
	v_mbcnt_hi_u32_b32 v2, s7, v2
	v_cmp_eq_u32_e64 s[0:1], 0, v2
	s_and_b64 s[0:1], exec, s[0:1]
	s_mov_b64 exec, s[0:1]
	s_bcnt1_i32_b64 s0, s[6:7]
	v_mov_b32_e32 v2, s0
	ds_add_u32 v196, v2
